# h1/h3: batch the 32 serialized LDS u16 reads per thread; h1: lb load before tile prefetch so prefetch stays in flight
# speedup vs baseline: 1.0085x; 1.0085x over previous
.LBB0_306:
	s_or_b64 exec, exec, s[0:1]
	s_waitcnt lgkmcnt(0)
	s_barrier
	ds_read_u16 v1, v114
	ds_read_u16 v193, v114 offset:272
	ds_read_u16 v194, v114 offset:544
	ds_read_u16 v195, v114 offset:816
	ds_read_u16 v196, v114 offset:1088
	ds_read_u16 v197, v114 offset:1360
	ds_read_u16 v198, v114 offset:1632
	ds_read_u16 v199, v114 offset:1904
	ds_read_u16 v200, v114 offset:2176
	ds_read_u16 v201, v114 offset:2448
	ds_read_u16 v202, v114 offset:2720
	ds_read_u16 v203, v114 offset:2992
	ds_read_u16 v204, v114 offset:3264
	ds_read_u16 v205, v114 offset:3536
	ds_read_u16 v206, v114 offset:3808
	ds_read_u16 v207, v114 offset:4080
	ds_read_u16 v177, v114 offset:34816
	ds_read_u16 v178, v119 offset:34816
	ds_read_u16 v179, v119 offset:35088
	ds_read_u16 v180, v119 offset:35360
	ds_read_u16 v181, v119 offset:35632
	ds_read_u16 v182, v119 offset:35904
	ds_read_u16 v183, v119 offset:36176
	ds_read_u16 v184, v119 offset:36448
	ds_read_u16 v185, v119 offset:36720
	ds_read_u16 v186, v119 offset:36992
	ds_read_u16 v187, v119 offset:37264
	ds_read_u16 v188, v119 offset:37536
	ds_read_u16 v189, v119 offset:37808
	ds_read_u16 v190, v119 offset:38080
	ds_read_u16 v191, v119 offset:38352
	ds_read_u16 v192, v119 offset:38624
	v_sub_f32_e32 v2, 1.0, v0
	s_mov_b32 s5, 0x800000
	s_mov_b32 s8, 0x3f317217
	s_mov_b32 s9, 0x7f800000
	s_waitcnt lgkmcnt(0)
	v_lshlrev_b32_e32 v1, 16, v1
	v_mul_f32_e32 v1, 0xbfb8aa3b, v1
	v_exp_f32_e32 v153, v1
	v_ashrrev_i32_e32 v109, 31, v108
	v_mov_b32_e32 v174, 0
	v_add_f32_e32 v1, 1.0, v153
	v_rcp_f32_e32 v155, v1
	s_nop 0
	v_fma_f32 v1, v2, v155, v0
	v_cmp_gt_f32_e32 vcc, s5, v1
	s_nop 1
	v_cndmask_b32_e64 v3, 0, 32, vcc
	v_ldexp_f32 v1, v1, v3
	v_log_f32_e32 v1, v1
	s_nop 0
	v_mul_f32_e32 v3, 0x3f317217, v1
	v_fma_f32 v3, v1, s8, -v3
	v_fmac_f32_e32 v3, 0x3377d1cf, v1
	v_fmac_f32_e32 v3, 0x3f317217, v1
	v_cmp_lt_f32_e64 s[0:1], |v1|, s9
	s_nop 1
	v_cndmask_b32_e64 v1, v1, v3, s[0:1]
	v_cndmask_b32_e32 v3, 0, v227, vcc
	v_sub_f32_e32 v1, v1, v3
	v_add_f32_e32 v97, 0, v1
	v_mov_b32_e32 v1, v193
	s_waitcnt lgkmcnt(0)
	v_lshlrev_b32_e32 v1, 16, v1
	v_mul_f32_e32 v1, 0xbfb8aa3b, v1
	v_exp_f32_e32 v151, v1
	s_nop 0
	v_add_f32_e32 v1, 1.0, v151
	v_rcp_f32_e32 v154, v1
	s_nop 0
	v_fma_f32 v1, v2, v154, v0
	v_cmp_gt_f32_e32 vcc, s5, v1
	s_nop 1
	v_cndmask_b32_e64 v3, 0, 32, vcc
	v_ldexp_f32 v1, v1, v3
	v_log_f32_e32 v1, v1
	s_nop 0
	v_mul_f32_e32 v3, 0x3f317217, v1
	v_fma_f32 v3, v1, s8, -v3
	v_fmac_f32_e32 v3, 0x3377d1cf, v1
	v_fmac_f32_e32 v3, 0x3f317217, v1
	v_cmp_lt_f32_e64 s[0:1], |v1|, s9
	s_nop 1
	v_cndmask_b32_e64 v1, v1, v3, s[0:1]
	v_cndmask_b32_e32 v3, 0, v227, vcc
	v_sub_f32_e32 v1, v1, v3
	v_add_f32_e32 v93, v97, v1
	v_mov_b32_e32 v1, v194
	s_waitcnt lgkmcnt(0)
	v_lshlrev_b32_e32 v1, 16, v1
	v_mul_f32_e32 v1, 0xbfb8aa3b, v1
	v_exp_f32_e32 v163, v1
	s_nop 0
	v_add_f32_e32 v1, 1.0, v163
	v_rcp_f32_e32 v164, v1
	s_nop 0
	v_fma_f32 v1, v2, v164, v0
	v_cmp_gt_f32_e32 vcc, s5, v1
	s_nop 1
	v_cndmask_b32_e64 v3, 0, 32, vcc
	v_ldexp_f32 v1, v1, v3
	v_log_f32_e32 v1, v1
	s_nop 0
	v_mul_f32_e32 v3, 0x3f317217, v1
	v_fma_f32 v3, v1, s8, -v3
	v_fmac_f32_e32 v3, 0x3377d1cf, v1
	v_fmac_f32_e32 v3, 0x3f317217, v1
	v_cmp_lt_f32_e64 s[0:1], |v1|, s9
	s_nop 1
	v_cndmask_b32_e64 v1, v1, v3, s[0:1]
	v_cndmask_b32_e32 v3, 0, v227, vcc
	v_sub_f32_e32 v1, v1, v3
	v_add_f32_e32 v149, v93, v1
	v_mov_b32_e32 v1, v195
	s_waitcnt lgkmcnt(0)
	v_lshlrev_b32_e32 v1, 16, v1
	v_mul_f32_e32 v1, 0xbfb8aa3b, v1
	v_exp_f32_e32 v161, v1
	s_nop 0
	v_add_f32_e32 v1, 1.0, v161
	v_rcp_f32_e32 v162, v1
	s_nop 0
	v_fma_f32 v1, v2, v162, v0
	v_cmp_gt_f32_e32 vcc, s5, v1
	s_nop 1
	v_cndmask_b32_e64 v3, 0, 32, vcc
	v_ldexp_f32 v1, v1, v3
	v_log_f32_e32 v1, v1
	s_nop 0
	v_mul_f32_e32 v3, 0x3f317217, v1
	v_fma_f32 v3, v1, s8, -v3
	v_fmac_f32_e32 v3, 0x3377d1cf, v1
	v_fmac_f32_e32 v3, 0x3f317217, v1
	v_cmp_lt_f32_e64 s[0:1], |v1|, s9
	s_nop 1
	v_cndmask_b32_e64 v1, v1, v3, s[0:1]
	v_cndmask_b32_e32 v3, 0, v227, vcc
	v_sub_f32_e32 v1, v1, v3
	v_add_f32_e32 v107, v149, v1
	v_mov_b32_e32 v1, v196
	s_waitcnt lgkmcnt(0)
	v_lshlrev_b32_e32 v1, 16, v1
	v_mul_f32_e32 v1, 0xbfb8aa3b, v1
	v_exp_f32_e32 v157, v1
	s_nop 0
	v_add_f32_e32 v1, 1.0, v157
	v_rcp_f32_e32 v159, v1
	s_nop 0
	v_fma_f32 v1, v2, v159, v0
	v_cmp_gt_f32_e32 vcc, s5, v1
	s_nop 1
	v_cndmask_b32_e64 v3, 0, 32, vcc
	v_ldexp_f32 v1, v1, v3
	v_log_f32_e32 v1, v1
	s_nop 0
	v_mul_f32_e32 v3, 0x3f317217, v1
	v_fma_f32 v3, v1, s8, -v3
	v_fmac_f32_e32 v3, 0x3377d1cf, v1
	v_fmac_f32_e32 v3, 0x3f317217, v1
	v_cmp_lt_f32_e64 s[0:1], |v1|, s9
	s_nop 1
	v_cndmask_b32_e64 v1, v1, v3, s[0:1]
	v_cndmask_b32_e32 v3, 0, v227, vcc
	v_sub_f32_e32 v1, v1, v3
	v_add_f32_e32 v94, v107, v1
	v_mov_b32_e32 v1, v197
	s_waitcnt lgkmcnt(0)
	v_lshlrev_b32_e32 v1, 16, v1
	v_mul_f32_e32 v1, 0xbfb8aa3b, v1
	v_exp_f32_e32 v158, v1
	s_nop 0
	v_add_f32_e32 v1, 1.0, v158
	v_rcp_f32_e32 v160, v1
	s_nop 0
	v_fma_f32 v1, v2, v160, v0
	v_cmp_gt_f32_e32 vcc, s5, v1
	s_nop 1
	v_cndmask_b32_e64 v3, 0, 32, vcc
	v_ldexp_f32 v1, v1, v3
	v_log_f32_e32 v1, v1
	s_nop 0
	v_mul_f32_e32 v3, 0x3f317217, v1
	v_fma_f32 v3, v1, s8, -v3
	v_fmac_f32_e32 v3, 0x3377d1cf, v1
	v_fmac_f32_e32 v3, 0x3f317217, v1
	v_cmp_lt_f32_e64 s[0:1], |v1|, s9
	s_nop 1
	v_cndmask_b32_e64 v1, v1, v3, s[0:1]
	v_cndmask_b32_e32 v3, 0, v227, vcc
	v_sub_f32_e32 v1, v1, v3
	v_add_f32_e32 v95, v94, v1
	v_mov_b32_e32 v1, v198
	s_waitcnt lgkmcnt(0)
	v_lshlrev_b32_e32 v1, 16, v1
	v_mul_f32_e32 v1, 0xbfb8aa3b, v1
	v_exp_f32_e32 v150, v1
	s_nop 0
	v_add_f32_e32 v1, 1.0, v150
	v_rcp_f32_e32 v152, v1
	s_nop 0
	v_fma_f32 v1, v2, v152, v0
	v_cmp_gt_f32_e32 vcc, s5, v1
	s_nop 1
	v_cndmask_b32_e64 v3, 0, 32, vcc
	v_ldexp_f32 v1, v1, v3
	v_log_f32_e32 v1, v1
	s_nop 0
	v_mul_f32_e32 v3, 0x3f317217, v1
	v_fma_f32 v3, v1, s8, -v3
	v_fmac_f32_e32 v3, 0x3377d1cf, v1
	v_fmac_f32_e32 v3, 0x3f317217, v1
	v_cmp_lt_f32_e64 s[0:1], |v1|, s9
	s_nop 1
	v_cndmask_b32_e64 v1, v1, v3, s[0:1]
	v_cndmask_b32_e32 v3, 0, v227, vcc
	v_sub_f32_e32 v1, v1, v3
	v_add_f32_e32 v92, v95, v1
	v_mov_b32_e32 v1, v199
	s_waitcnt lgkmcnt(0)
	v_lshlrev_b32_e32 v1, 16, v1
	v_mul_f32_e32 v1, 0xbfb8aa3b, v1
	v_exp_f32_e32 v90, v1
	s_nop 0
	v_add_f32_e32 v1, 1.0, v90
	v_rcp_f32_e32 v91, v1
	s_nop 0
	v_fma_f32 v1, v2, v91, v0
	v_cmp_gt_f32_e32 vcc, s5, v1
	s_nop 1
	v_cndmask_b32_e64 v3, 0, 32, vcc
	v_ldexp_f32 v1, v1, v3
	v_log_f32_e32 v1, v1
	s_nop 0
	v_mul_f32_e32 v3, 0x3f317217, v1
	v_fma_f32 v3, v1, s8, -v3
	v_fmac_f32_e32 v3, 0x3377d1cf, v1
	v_fmac_f32_e32 v3, 0x3f317217, v1
	v_cmp_lt_f32_e64 s[0:1], |v1|, s9
	s_nop 1
	v_cndmask_b32_e64 v1, v1, v3, s[0:1]
	v_cndmask_b32_e32 v3, 0, v227, vcc
	v_sub_f32_e32 v1, v1, v3
	v_add_f32_e32 v88, v92, v1
	v_mov_b32_e32 v1, v200
	s_waitcnt lgkmcnt(0)
	v_lshlrev_b32_e32 v1, 16, v1
	v_mul_f32_e32 v1, 0xbfb8aa3b, v1
	v_exp_f32_e32 v86, v1
	s_nop 0
	v_add_f32_e32 v1, 1.0, v86
	v_rcp_f32_e32 v87, v1
	s_nop 0
	v_fma_f32 v1, v2, v87, v0
	v_cmp_gt_f32_e32 vcc, s5, v1
	s_nop 1
	v_cndmask_b32_e64 v3, 0, 32, vcc
	v_ldexp_f32 v1, v1, v3
	v_log_f32_e32 v1, v1
	s_nop 0
	v_mul_f32_e32 v3, 0x3f317217, v1
	v_fma_f32 v3, v1, s8, -v3
	v_fmac_f32_e32 v3, 0x3377d1cf, v1
	v_fmac_f32_e32 v3, 0x3f317217, v1
	v_cmp_lt_f32_e64 s[0:1], |v1|, s9
	s_nop 1
	v_cndmask_b32_e64 v1, v1, v3, s[0:1]
	v_cndmask_b32_e32 v3, 0, v227, vcc
	v_sub_f32_e32 v1, v1, v3
	v_add_f32_e32 v85, v88, v1
	v_mov_b32_e32 v1, v201
	s_waitcnt lgkmcnt(0)
	v_lshlrev_b32_e32 v1, 16, v1
	v_mul_f32_e32 v1, 0xbfb8aa3b, v1
	v_exp_f32_e32 v82, v1
	s_nop 0
	v_add_f32_e32 v1, 1.0, v82
	v_rcp_f32_e32 v83, v1
	s_nop 0
	v_fma_f32 v1, v2, v83, v0
	v_cmp_gt_f32_e32 vcc, s5, v1
	s_nop 1
	v_cndmask_b32_e64 v3, 0, 32, vcc
	v_ldexp_f32 v1, v1, v3
	v_log_f32_e32 v1, v1
	s_nop 0
	v_mul_f32_e32 v3, 0x3f317217, v1
	v_fma_f32 v3, v1, s8, -v3
	v_fmac_f32_e32 v3, 0x3377d1cf, v1
	v_fmac_f32_e32 v3, 0x3f317217, v1
	v_cmp_lt_f32_e64 s[0:1], |v1|, s9
	s_nop 1
	v_cndmask_b32_e64 v1, v1, v3, s[0:1]
	v_cndmask_b32_e32 v3, 0, v227, vcc
	v_sub_f32_e32 v1, v1, v3
	v_add_f32_e32 v81, v85, v1
	v_mov_b32_e32 v1, v202
	s_waitcnt lgkmcnt(0)
	v_lshlrev_b32_e32 v1, 16, v1
	v_mul_f32_e32 v1, 0xbfb8aa3b, v1
	v_exp_f32_e32 v78, v1
	s_nop 0
	v_add_f32_e32 v1, 1.0, v78
	v_rcp_f32_e32 v79, v1
	s_nop 0
	v_fma_f32 v1, v2, v79, v0
	v_cmp_gt_f32_e32 vcc, s5, v1
	s_nop 1
	v_cndmask_b32_e64 v3, 0, 32, vcc
	v_ldexp_f32 v1, v1, v3
	v_log_f32_e32 v1, v1
	s_nop 0
	v_mul_f32_e32 v3, 0x3f317217, v1
	v_fma_f32 v3, v1, s8, -v3
	v_fmac_f32_e32 v3, 0x3377d1cf, v1
	v_fmac_f32_e32 v3, 0x3f317217, v1
	v_cmp_lt_f32_e64 s[0:1], |v1|, s9
	s_nop 1
	v_cndmask_b32_e64 v1, v1, v3, s[0:1]
	v_cndmask_b32_e32 v3, 0, v227, vcc
	v_sub_f32_e32 v1, v1, v3
	v_add_f32_e32 v77, v81, v1
	v_mov_b32_e32 v1, v203
	s_waitcnt lgkmcnt(0)
	v_lshlrev_b32_e32 v1, 16, v1
	v_mul_f32_e32 v1, 0xbfb8aa3b, v1
	v_exp_f32_e32 v74, v1
	s_nop 0
	v_add_f32_e32 v1, 1.0, v74
	v_rcp_f32_e32 v75, v1
	s_nop 0
	v_fma_f32 v1, v2, v75, v0
	v_cmp_gt_f32_e32 vcc, s5, v1
	s_nop 1
	v_cndmask_b32_e64 v3, 0, 32, vcc
	v_ldexp_f32 v1, v1, v3
	v_log_f32_e32 v1, v1
	s_nop 0
	v_mul_f32_e32 v3, 0x3f317217, v1
	v_fma_f32 v3, v1, s8, -v3
	v_fmac_f32_e32 v3, 0x3377d1cf, v1
	v_fmac_f32_e32 v3, 0x3f317217, v1
	v_cmp_lt_f32_e64 s[0:1], |v1|, s9
	s_nop 1
	v_cndmask_b32_e64 v1, v1, v3, s[0:1]
	v_cndmask_b32_e32 v3, 0, v227, vcc
	v_sub_f32_e32 v1, v1, v3
	v_add_f32_e32 v73, v77, v1
	v_mov_b32_e32 v1, v204
	s_waitcnt lgkmcnt(0)
	v_lshlrev_b32_e32 v1, 16, v1
	v_mul_f32_e32 v1, 0xbfb8aa3b, v1
	v_exp_f32_e32 v15, v1
	s_nop 0
	v_add_f32_e32 v1, 1.0, v15
	v_rcp_f32_e32 v72, v1
	s_nop 0
	v_fma_f32 v1, v2, v72, v0
	v_cmp_gt_f32_e32 vcc, s5, v1
	s_nop 1
	v_cndmask_b32_e64 v3, 0, 32, vcc
	v_ldexp_f32 v1, v1, v3
	v_log_f32_e32 v1, v1
	s_nop 0
	v_mul_f32_e32 v3, 0x3f317217, v1
	v_fma_f32 v3, v1, s8, -v3
	v_fmac_f32_e32 v3, 0x3377d1cf, v1
	v_fmac_f32_e32 v3, 0x3f317217, v1
	v_cmp_lt_f32_e64 s[0:1], |v1|, s9
	s_nop 1
	v_cndmask_b32_e64 v1, v1, v3, s[0:1]
	v_cndmask_b32_e32 v3, 0, v227, vcc
	v_sub_f32_e32 v1, v1, v3
	v_add_f32_e32 v13, v73, v1
	v_mov_b32_e32 v1, v205
	s_waitcnt lgkmcnt(0)
	v_lshlrev_b32_e32 v1, 16, v1
	v_mul_f32_e32 v1, 0xbfb8aa3b, v1
	v_exp_f32_e32 v11, v1
	s_nop 0
	v_add_f32_e32 v1, 1.0, v11
	v_rcp_f32_e32 v12, v1
	s_nop 0
	v_fma_f32 v1, v2, v12, v0
	v_cmp_gt_f32_e32 vcc, s5, v1
	s_nop 1
	v_cndmask_b32_e64 v3, 0, 32, vcc
	v_ldexp_f32 v1, v1, v3
	v_log_f32_e32 v1, v1
	s_nop 0
	v_mul_f32_e32 v3, 0x3f317217, v1
	v_fma_f32 v3, v1, s8, -v3
	v_fmac_f32_e32 v3, 0x3377d1cf, v1
	v_fmac_f32_e32 v3, 0x3f317217, v1
	v_cmp_lt_f32_e64 s[0:1], |v1|, s9
	s_nop 1
	v_cndmask_b32_e64 v1, v1, v3, s[0:1]
	v_cndmask_b32_e32 v3, 0, v227, vcc
	v_sub_f32_e32 v1, v1, v3
	v_add_f32_e32 v10, v13, v1
	v_mov_b32_e32 v1, v206
	s_waitcnt lgkmcnt(0)
	v_lshlrev_b32_e32 v1, 16, v1
	v_mul_f32_e32 v1, 0xbfb8aa3b, v1
	v_exp_f32_e32 v7, v1
	s_nop 0
	v_add_f32_e32 v1, 1.0, v7
	v_rcp_f32_e32 v8, v1
	s_nop 0
	v_fma_f32 v1, v2, v8, v0
	v_cmp_gt_f32_e32 vcc, s5, v1
	s_nop 1
	v_cndmask_b32_e64 v3, 0, 32, vcc
	v_ldexp_f32 v1, v1, v3
	v_log_f32_e32 v1, v1
	s_nop 0
	v_mul_f32_e32 v3, 0x3f317217, v1
	v_fma_f32 v3, v1, s8, -v3
	v_fmac_f32_e32 v3, 0x3377d1cf, v1
	v_fmac_f32_e32 v3, 0x3f317217, v1
	v_cmp_lt_f32_e64 s[0:1], |v1|, s9
	s_nop 1
	v_cndmask_b32_e64 v1, v1, v3, s[0:1]
	v_cndmask_b32_e32 v3, 0, v227, vcc
	v_sub_f32_e32 v1, v1, v3
	v_add_f32_e32 v6, v10, v1
	v_mov_b32_e32 v1, v207
	ds_read_u16 v173, v114 offset:17408
	ds_read_u16 v172, v119 offset:17408
	ds_read_u16 v171, v119 offset:17680
	ds_read_u16 v170, v119 offset:17952
	ds_read_u16 v169, v119 offset:18224
	ds_read_u16 v168, v119 offset:18496
	ds_read_u16 v167, v119 offset:18768
	ds_read_u16 v166, v119 offset:19040
	ds_read_u16 v165, v119 offset:19312
	ds_read_u16 v156, v119 offset:19584
	ds_read_u16 v89, v119 offset:19856
	ds_read_u16 v84, v119 offset:20128
	ds_read_u16 v80, v119 offset:20400
	ds_read_u16 v76, v119 offset:20672
	ds_read_u16 v14, v119 offset:20944
	ds_read_u16 v9, v119 offset:21216
	s_waitcnt lgkmcnt(14)
	v_lshlrev_b32_e32 v1, 16, v1
	v_mul_f32_e32 v1, 0xbfb8aa3b, v1
	v_exp_f32_e32 v3, v1
	s_nop 0
	v_add_f32_e32 v1, 1.0, v3
	v_rcp_f32_e32 v4, v1
	s_nop 0
	v_fmac_f32_e32 v0, v2, v4
	v_cmp_gt_f32_e32 vcc, s5, v0
	s_nop 1
	v_cndmask_b32_e64 v1, 0, 32, vcc
	v_ldexp_f32 v0, v0, v1
	v_log_f32_e32 v0, v0
	s_nop 0
	v_mul_f32_e32 v1, 0x3f317217, v0
	v_fma_f32 v1, v0, s8, -v1
	v_fmac_f32_e32 v1, 0x3377d1cf, v0
	v_fmac_f32_e32 v1, 0x3f317217, v0
	v_cmp_lt_f32_e64 s[0:1], |v0|, s9
	s_nop 1
	v_cndmask_b32_e64 v0, v0, v1, s[0:1]
	v_cndmask_b32_e32 v1, 0, v227, vcc
	v_sub_f32_e32 v0, v0, v1
	v_add_f32_e32 v5, v6, v0
	ds_write_b32 v115, v5
	s_waitcnt lgkmcnt(1)
	ds_write_b16 v116, v177
	ds_write_b16 v116, v178 offset:2
	ds_write_b16 v116, v179 offset:4
	ds_write_b16 v116, v180 offset:6
	ds_write_b16 v116, v181 offset:8
	ds_write_b16 v116, v182 offset:10
	ds_write_b16 v116, v183 offset:12
	ds_write_b16 v116, v184 offset:14
	ds_write_b16 v116, v185 offset:16
	ds_write_b16 v116, v186 offset:18
	ds_write_b16 v116, v187 offset:20
	ds_write_b16 v116, v188 offset:22
	ds_write_b16 v116, v189 offset:24
	ds_write_b16 v116, v190 offset:26
	ds_write_b16 v116, v191 offset:28
	ds_write_b16 v116, v192 offset:30
	s_waitcnt lgkmcnt(0)
	s_barrier
	ds_read2st64_b32 v[0:1], v117 offset0:2 offset1:4
	s_and_saveexec_b64 s[0:1], s[38:39]
	s_cbranch_execz .LBB0_314
	ds_read_b32 v175, v117
	v_cmp_lt_i32_e32 vcc, 1, v111
	s_mov_b64 s[8:9], 0
	s_and_saveexec_b64 s[10:11], vcc
	s_xor_b64 s[10:11], exec, s[10:11]
	s_cbranch_execz .LBB0_395
	v_cmp_eq_u32_e32 vcc, 2, v111
	s_mov_b64 s[8:9], -1
	s_and_saveexec_b64 s[12:13], vcc
	s_cbranch_execz .LBB0_310
	s_waitcnt lgkmcnt(0)
	v_add_f32_e32 v174, v175, v0
	s_xor_b64 s[8:9], exec, -1

.LBB0_542:
	s_or_b64 exec, exec, s[8:9]
	s_waitcnt lgkmcnt(0)
	s_barrier
	ds_read_b128 v[16:19], v76 offset:18432
	ds_read_b128 v[0:3], v77
	ds_read_b128 v[20:23], v77 offset:4608
	s_waitcnt lgkmcnt(1)
	v_mfma_f32_32x32x16_bf16 v[0:15], v[16:19], v[0:3], 0
	ds_read_b128 v[84:87], v76 offset:18464
	ds_read_b128 v[88:91], v77 offset:32
	s_ashr_i32 s15, s14, 31
	s_lshl_b64 s[8:9], s[14:15], 15
	s_add_u32 s8, s22, s8
	s_addc_u32 s9, s23, s9
	v_mov_b32_e32 v63, v209
	s_add_i32 s26, s26, s27
	s_waitcnt lgkmcnt(2)
	v_mfma_f32_32x32x16_bf16 v[16:31], v[16:19], v[20:23], 0
	s_add_i32 s14, s14, s17
	v_add_u32_e32 v60, s28, v60
	s_cmp_lg_u32 s19, s29
	s_waitcnt lgkmcnt(0)
	v_mfma_f32_32x32x16_bf16 v[0:15], v[84:87], v[88:91], v[0:15]
	ds_read_b128 v[88:91], v77 offset:4640
	s_waitcnt lgkmcnt(0)
	v_mfma_f32_32x32x16_bf16 v[16:31], v[84:87], v[88:91], v[16:31]
	ds_read_b128 v[84:87], v76 offset:18496
	ds_read_b128 v[88:91], v77 offset:64
	s_waitcnt lgkmcnt(0)
	v_mfma_f32_32x32x16_bf16 v[0:15], v[84:87], v[88:91], v[0:15]
	ds_read_b128 v[88:91], v77 offset:4672
	s_waitcnt lgkmcnt(0)
	v_mfma_f32_32x32x16_bf16 v[16:31], v[84:87], v[88:91], v[16:31]
	ds_read_b128 v[84:87], v76 offset:18528
	ds_read_b128 v[88:91], v77 offset:96
	s_waitcnt lgkmcnt(0)
	v_mfma_f32_32x32x16_bf16 v[0:15], v[84:87], v[88:91], v[0:15]
	ds_read_b128 v[88:91], v77 offset:4704
	s_waitcnt lgkmcnt(0)
	v_mfma_f32_32x32x16_bf16 v[16:31], v[84:87], v[88:91], v[16:31]
	s_nop 8
	v_cvt_pk_bf16_f32 v0, v0, s0
	ds_write_b16 v75, v0 offset:38912
	s_nop 0
	v_cvt_pk_bf16_f32 v0, v16, s0
	ds_write_b16 v75, v0 offset:38976
	v_cvt_pk_bf16_f32 v0, v1, s0
	ds_write_b16 v75, v0 offset:39184
	v_cvt_pk_bf16_f32 v0, v17, s0
	ds_write_b16 v75, v0 offset:39248
	v_cvt_pk_bf16_f32 v0, v2, s0
	ds_write_b16 v75, v0 offset:39456
	v_cvt_pk_bf16_f32 v0, v18, s0
	ds_write_b16 v75, v0 offset:39520
	v_cvt_pk_bf16_f32 v0, v3, s0
	ds_write_b16 v75, v0 offset:39728
	v_cvt_pk_bf16_f32 v0, v19, s0
	ds_write_b16 v75, v0 offset:39792
	v_cvt_pk_bf16_f32 v0, v4, s0
	ds_write_b16 v75, v0 offset:41088
	v_cvt_pk_bf16_f32 v0, v20, s0
	ds_write_b16 v75, v0 offset:41152
	v_cvt_pk_bf16_f32 v0, v5, s0
	ds_write_b16 v75, v0 offset:41360
	v_cvt_pk_bf16_f32 v0, v21, s0
	ds_write_b16 v75, v0 offset:41424
	v_cvt_pk_bf16_f32 v0, v6, s0
	ds_write_b16 v75, v0 offset:41632
	v_cvt_pk_bf16_f32 v0, v22, s0
	ds_write_b16 v75, v0 offset:41696
	v_cvt_pk_bf16_f32 v0, v7, s0
	ds_write_b16 v75, v0 offset:41904
	v_cvt_pk_bf16_f32 v0, v23, s0
	ds_write_b16 v75, v0 offset:41968
	v_cvt_pk_bf16_f32 v0, v8, s0
	ds_write_b16 v75, v0 offset:43264
	v_cvt_pk_bf16_f32 v0, v24, s0
	ds_write_b16 v75, v0 offset:43328
	v_cvt_pk_bf16_f32 v0, v9, s0
	ds_write_b16 v75, v0 offset:43536
	v_cvt_pk_bf16_f32 v0, v25, s0
	ds_write_b16 v75, v0 offset:43600
	v_cvt_pk_bf16_f32 v0, v10, s0
	ds_write_b16 v75, v0 offset:43808
	v_cvt_pk_bf16_f32 v0, v26, s0
	ds_write_b16 v75, v0 offset:43872
	v_cvt_pk_bf16_f32 v0, v11, s0
	ds_write_b16 v75, v0 offset:44080
	v_cvt_pk_bf16_f32 v0, v27, s0
	ds_write_b16 v75, v0 offset:44144
	v_cvt_pk_bf16_f32 v0, v12, s0
	ds_write_b16 v75, v0 offset:45440
	v_cvt_pk_bf16_f32 v0, v28, s0
	ds_write_b16 v75, v0 offset:45504
	v_cvt_pk_bf16_f32 v0, v13, s0
	ds_write_b16 v75, v0 offset:45712
	v_cvt_pk_bf16_f32 v0, v29, s0
	ds_write_b16 v75, v0 offset:45776
	v_cvt_pk_bf16_f32 v0, v14, s0
	ds_write_b16 v75, v0 offset:45984
	v_cvt_pk_bf16_f32 v0, v30, s0
	ds_write_b16 v75, v0 offset:46048
	v_cvt_pk_bf16_f32 v0, v15, s0
	ds_write_b16 v75, v0 offset:46256
	v_cvt_pk_bf16_f32 v0, v31, s0
	ds_write_b16 v75, v0 offset:46320
	s_waitcnt lgkmcnt(0)
	s_barrier
	ds_read_b128 v[0:3], v78 offset:38912
	v_lshl_add_u64 v[4:5], v[52:53], 1, s[8:9]
	v_lshl_add_u64 v[8:9], v[4:5], 0, v[62:63]
	ds_read_b128 v[4:7], v79 offset:38912
	s_waitcnt vmcnt(0)
	v_mov_b64_e32 v[12:13], v[36:37]
	s_waitcnt lgkmcnt(1)
	global_store_dwordx4 v[8:9], v[0:3], off
	v_mov_b64_e32 v[14:15], v[38:39]
	s_nop 0
	v_lshl_add_u64 v[0:1], v[54:55], 1, s[8:9]
	v_lshl_add_u64 v[8:9], v[0:1], 0, v[62:63]
	ds_read_b128 v[0:3], v82 offset:38912
	s_waitcnt lgkmcnt(1)
	global_store_dwordx4 v[8:9], v[4:7], off
	ds_read_b128 v[4:7], v83 offset:38912
	v_lshl_add_u64 v[8:9], v[56:57], 1, s[8:9]
	v_lshl_add_u64 v[8:9], v[8:9], 0, v[62:63]
	s_waitcnt lgkmcnt(1)
	global_store_dwordx4 v[8:9], v[0:3], off
	v_mov_b64_e32 v[8:9], v[44:45]
	v_mov_b64_e32 v[10:11], v[46:47]
	v_lshl_add_u64 v[0:1], v[58:59], 1, s[8:9]
	v_lshl_add_u64 v[0:1], v[0:1], 0, v[62:63]
	s_waitcnt lgkmcnt(0)
	global_store_dwordx4 v[0:1], v[4:7], off
	v_mov_b64_e32 v[0:1], v[40:41]
	v_mov_b64_e32 v[2:3], v[42:43]
	v_mov_b64_e32 v[4:5], v[32:33]
	v_mov_b64_e32 v[6:7], v[34:35]
	s_cbranch_scc0 .LBB0_553
.LBB0_543:
	v_readlane_b32 s8, v251, 41
	v_readlane_b32 s9, v251, 42
	v_mov_b32_e32 v61, 0
	s_andn2_b64 vcc, exec, s[8:9]
	s_waitcnt vmcnt(9)
	v_mov_b32_e32 v89, 0
	s_cbranch_vccnz .LBB0_545
	s_and_b32 s8, s26, 0x180
	v_or_b32_e32 v16, s8, v66
	v_lshlrev_b32_e32 v16, 2, v16
	v_mov_b32_e32 v17, v209
	v_lshl_add_u64 v[16:17], s[10:11], 0, v[16:17]
	v_add_co_u32_e32 v16, vcc, 0x101000, v16
	s_nop 1
	v_addc_co_u32_e32 v17, vcc, 0, v17, vcc
	global_load_dword v89, v[16:17], off
.LBB0_545:
	s_mov_b32 s8, s29
	s_add_i32 s29, s29, 1
	s_cmp_lt_i32 s29, s19
	s_cselect_b32 s8, s29, s8
	s_mul_i32 s8, s8, s17
	s_add_i32 s8, s8, s16
	s_lshl_b32 s9, s8, 4
	s_lshl_b32 s15, s8, 6
	s_and_b32 s9, s9, 0x3000
	s_and_b32 s15, s15, 0xfc0
	s_or_b32 s9, s9, s15
	s_mulk_i32 s9, 0x1800
	s_add_u32 s9, s20, s9
	s_addc_u32 s15, s21, 0
	s_lshl_b32 s8, s8, 2
	s_and_b32 s8, s8, 0x300
	s_add_u32 s8, s9, s8
	s_addc_u32 s9, s15, 0
	v_lshl_add_u64 v[16:17], s[8:9], 0, v[208:209]
	v_lshl_add_u64 v[18:19], v[16:17], 0, v[48:49]
	v_lshl_add_u64 v[16:17], v[16:17], 0, v[50:51]
	global_load_dwordx4 v[32:35], v[18:19], off offset:2048
	global_load_dwordx4 v[40:43], v[16:17], off offset:2048
	global_load_dwordx4 v[36:39], v[18:19], off offset:3072
	global_load_dwordx4 v[44:47], v[16:17], off offset:3072
	v_add_u32_e32 v16, v67, v68
	s_barrier
	s_waitcnt vmcnt(7)
	ds_write_b128 v16, v[4:7] offset:38912
	v_add_u32_e32 v4, v67, v69
	s_waitcnt vmcnt(6)
	ds_write_b128 v4, v[0:3] offset:38912
	s_waitcnt vmcnt(5)
	ds_write_b128 v16, v[12:15] offset:56320
	s_waitcnt vmcnt(4)
	ds_write_b128 v4, v[8:11] offset:56320
	s_waitcnt lgkmcnt(0)
	s_barrier
	ds_read_u16 v1, v70 offset:38912
	ds_read_u16 v198, v70 offset:39184
	ds_read_u16 v199, v70 offset:39456
	ds_read_u16 v200, v70 offset:39728
	ds_read_u16 v201, v70 offset:40000
	ds_read_u16 v202, v70 offset:40272
	ds_read_u16 v203, v70 offset:40544
	ds_read_u16 v204, v70 offset:40816
	ds_read_u16 v205, v70 offset:41088
	ds_read_u16 v206, v70 offset:41360
	ds_read_u16 v207, v70 offset:41632
	ds_read_u16 v216, v70 offset:41904
	ds_read_u16 v217, v70 offset:42176
	ds_read_u16 v218, v70 offset:42448
	ds_read_u16 v219, v70 offset:42720
	ds_read_u16 v220, v70 offset:42992
	ds_read_u16 v221, v70 offset:56320
	ds_read_u16 v223, v70 offset:56592
	ds_read_u16 v224, v70 offset:56864
	ds_read_u16 v225, v70 offset:57136
	ds_read_u16 v229, v70 offset:57408
	ds_read_u16 v230, v70 offset:57680
	ds_read_u16 v232, v70 offset:57952
	ds_read_u16 v239, v70 offset:58224
	ds_read_u16 v240, v70 offset:58496
	ds_read_u16 v241, v70 offset:58768
	ds_read_u16 v242, v70 offset:59040
	ds_read_u16 v243, v70 offset:59312
	ds_read_u16 v244, v70 offset:59584
	ds_read_u16 v245, v70 offset:59856
	ds_read_u16 v246, v70 offset:60128
	ds_read_u16 v247, v70 offset:60400
	s_waitcnt vmcnt(4)
	v_sub_f32_e32 v0, 1.0, v89
	s_mov_b32 s15, 0x800000
	s_mov_b32 s30, 0x3f317217
	s_mov_b32 s31, 0x7f800000
	s_waitcnt lgkmcnt(0)
	v_lshlrev_b32_e32 v1, 16, v1
	v_mul_f32_e32 v1, 0xbfb8aa3b, v1
	v_exp_f32_e32 v4, v1
	s_nop 0
	v_add_f32_e32 v1, 1.0, v4
	v_rcp_f32_e32 v2, v1
	s_nop 0
	v_fma_f32 v1, v0, v2, v89
	v_cmp_gt_f32_e32 vcc, s15, v1
	s_nop 1
	v_cndmask_b32_e64 v3, 0, 32, vcc
	v_ldexp_f32 v1, v1, v3
	v_log_f32_e32 v1, v1
	s_nop 0
	v_mul_f32_e32 v3, 0x3f317217, v1
	v_fma_f32 v3, v1, s30, -v3
	v_fmac_f32_e32 v3, 0x3377d1cf, v1
	v_fmac_f32_e32 v3, 0x3f317217, v1
	v_cmp_lt_f32_e64 s[8:9], |v1|, s31
	s_nop 1
	v_cndmask_b32_e64 v1, v1, v3, s[8:9]
	v_cndmask_b32_e32 v3, 0, v227, vcc
	v_sub_f32_e32 v1, v1, v3
	v_mov_b32_e32 v3, v198
	v_add_f32_e32 v1, 0, v1
	s_waitcnt lgkmcnt(0)
	v_lshlrev_b32_e32 v3, 16, v3
	v_mul_f32_e32 v3, 0xbfb8aa3b, v3
	v_exp_f32_e32 v5, v3
	s_nop 0
	v_add_f32_e32 v3, 1.0, v5
	v_rcp_f32_e32 v3, v3
	s_nop 0
	v_fma_f32 v6, v0, v3, v89
	v_cmp_gt_f32_e32 vcc, s15, v6
	s_nop 1
	v_cndmask_b32_e64 v7, 0, 32, vcc
	v_ldexp_f32 v6, v6, v7
	v_log_f32_e32 v6, v6
	s_nop 0
	v_mul_f32_e32 v7, 0x3f317217, v6
	v_fma_f32 v7, v6, s30, -v7
	v_fmac_f32_e32 v7, 0x3377d1cf, v6
	v_fmac_f32_e32 v7, 0x3f317217, v6
	v_cmp_lt_f32_e64 s[8:9], |v6|, s31
	s_nop 1
	v_cndmask_b32_e64 v6, v6, v7, s[8:9]
	v_cndmask_b32_e32 v7, 0, v227, vcc
	v_sub_f32_e32 v6, v6, v7
	v_add_f32_e32 v63, v1, v6
	v_mov_b32_e32 v6, v199
	s_waitcnt lgkmcnt(0)
	v_lshlrev_b32_e32 v6, 16, v6
	v_mul_f32_e32 v6, 0xbfb8aa3b, v6
	v_exp_f32_e32 v8, v6
	s_nop 0
	v_add_f32_e32 v6, 1.0, v8
	v_rcp_f32_e32 v6, v6
	s_nop 0
	v_fma_f32 v7, v0, v6, v89
	v_cmp_gt_f32_e32 vcc, s15, v7
	s_nop 1
	v_cndmask_b32_e64 v9, 0, 32, vcc
	v_ldexp_f32 v7, v7, v9
	v_log_f32_e32 v7, v7
	s_nop 0
	v_mul_f32_e32 v9, 0x3f317217, v7
	v_fma_f32 v9, v7, s30, -v9
	v_fmac_f32_e32 v9, 0x3377d1cf, v7
	v_fmac_f32_e32 v9, 0x3f317217, v7
	v_cmp_lt_f32_e64 s[8:9], |v7|, s31
	s_nop 1
	v_cndmask_b32_e64 v7, v7, v9, s[8:9]
	v_cndmask_b32_e32 v9, 0, v227, vcc
	v_sub_f32_e32 v7, v7, v9
	v_add_f32_e32 v84, v63, v7
	v_mov_b32_e32 v7, v200
	s_waitcnt lgkmcnt(0)
	v_lshlrev_b32_e32 v7, 16, v7
	v_mul_f32_e32 v7, 0xbfb8aa3b, v7
	v_exp_f32_e32 v9, v7
	s_nop 0
	v_add_f32_e32 v7, 1.0, v9
	v_rcp_f32_e32 v7, v7
	s_nop 0
	v_fma_f32 v10, v0, v7, v89
	v_cmp_gt_f32_e32 vcc, s15, v10
	s_nop 1
	v_cndmask_b32_e64 v11, 0, 32, vcc
	v_ldexp_f32 v10, v10, v11
	v_log_f32_e32 v10, v10
	s_nop 0
	v_mul_f32_e32 v11, 0x3f317217, v10
	v_fma_f32 v11, v10, s30, -v11
	v_fmac_f32_e32 v11, 0x3377d1cf, v10
	v_fmac_f32_e32 v11, 0x3f317217, v10
	v_cmp_lt_f32_e64 s[8:9], |v10|, s31
	s_nop 1
	v_cndmask_b32_e64 v10, v10, v11, s[8:9]
	v_cndmask_b32_e32 v11, 0, v227, vcc
	v_sub_f32_e32 v10, v10, v11
	v_add_f32_e32 v85, v84, v10
	v_mov_b32_e32 v10, v201
	s_waitcnt lgkmcnt(0)
	v_lshlrev_b32_e32 v10, 16, v10
	v_mul_f32_e32 v10, 0xbfb8aa3b, v10
	v_exp_f32_e32 v12, v10
	s_nop 0
	v_add_f32_e32 v10, 1.0, v12
	v_rcp_f32_e32 v10, v10
	s_nop 0
	v_fma_f32 v11, v0, v10, v89
	v_cmp_gt_f32_e32 vcc, s15, v11
	s_nop 1
	v_cndmask_b32_e64 v13, 0, 32, vcc
	v_ldexp_f32 v11, v11, v13
	v_log_f32_e32 v11, v11
	s_nop 0
	v_mul_f32_e32 v13, 0x3f317217, v11
	v_fma_f32 v13, v11, s30, -v13
	v_fmac_f32_e32 v13, 0x3377d1cf, v11
	v_fmac_f32_e32 v13, 0x3f317217, v11
	v_cmp_lt_f32_e64 s[8:9], |v11|, s31
	s_nop 1
	v_cndmask_b32_e64 v11, v11, v13, s[8:9]
	v_cndmask_b32_e32 v13, 0, v227, vcc
	v_sub_f32_e32 v11, v11, v13
	v_add_f32_e32 v86, v85, v11
	v_mov_b32_e32 v11, v202
	s_waitcnt lgkmcnt(0)
	v_lshlrev_b32_e32 v11, 16, v11
	v_mul_f32_e32 v11, 0xbfb8aa3b, v11
	v_exp_f32_e32 v13, v11
	s_nop 0
	v_add_f32_e32 v11, 1.0, v13
	v_rcp_f32_e32 v11, v11
	s_nop 0
	v_fma_f32 v14, v0, v11, v89
	v_cmp_gt_f32_e32 vcc, s15, v14
	s_nop 1
	v_cndmask_b32_e64 v15, 0, 32, vcc
	v_ldexp_f32 v14, v14, v15
	v_log_f32_e32 v14, v14
	s_nop 0
	v_mul_f32_e32 v15, 0x3f317217, v14
	v_fma_f32 v15, v14, s30, -v15
	v_fmac_f32_e32 v15, 0x3377d1cf, v14
	v_fmac_f32_e32 v15, 0x3f317217, v14
	v_cmp_lt_f32_e64 s[8:9], |v14|, s31
	s_nop 1
	v_cndmask_b32_e64 v14, v14, v15, s[8:9]
	v_cndmask_b32_e32 v15, 0, v227, vcc
	v_sub_f32_e32 v14, v14, v15
	v_add_f32_e32 v87, v86, v14
	v_mov_b32_e32 v14, v203
	s_waitcnt lgkmcnt(0)
	v_lshlrev_b32_e32 v14, 16, v14
	v_mul_f32_e32 v14, 0xbfb8aa3b, v14
	v_exp_f32_e32 v16, v14
	s_nop 0
	v_add_f32_e32 v14, 1.0, v16
	v_rcp_f32_e32 v14, v14
	s_nop 0
	v_fma_f32 v15, v0, v14, v89
	v_cmp_gt_f32_e32 vcc, s15, v15
	s_nop 1
	v_cndmask_b32_e64 v17, 0, 32, vcc
	v_ldexp_f32 v15, v15, v17
	v_log_f32_e32 v15, v15
	s_nop 0
	v_mul_f32_e32 v17, 0x3f317217, v15
	v_fma_f32 v17, v15, s30, -v17
	v_fmac_f32_e32 v17, 0x3377d1cf, v15
	v_fmac_f32_e32 v17, 0x3f317217, v15
	v_cmp_lt_f32_e64 s[8:9], |v15|, s31
	s_nop 1
	v_cndmask_b32_e64 v15, v15, v17, s[8:9]
	v_cndmask_b32_e32 v17, 0, v227, vcc
	v_sub_f32_e32 v15, v15, v17
	v_add_f32_e32 v88, v87, v15
	v_mov_b32_e32 v15, v204
	s_waitcnt lgkmcnt(0)
	v_lshlrev_b32_e32 v15, 16, v15
	v_mul_f32_e32 v15, 0xbfb8aa3b, v15
	v_exp_f32_e32 v17, v15
	s_nop 0
	v_add_f32_e32 v15, 1.0, v17
	v_rcp_f32_e32 v15, v15
	s_nop 0
	v_fma_f32 v18, v0, v15, v89
	v_cmp_gt_f32_e32 vcc, s15, v18
	s_nop 1
	v_cndmask_b32_e64 v19, 0, 32, vcc
	v_ldexp_f32 v18, v18, v19
	v_log_f32_e32 v18, v18
	s_nop 0
	v_mul_f32_e32 v19, 0x3f317217, v18
	v_fma_f32 v19, v18, s30, -v19
	v_fmac_f32_e32 v19, 0x3377d1cf, v18
	v_fmac_f32_e32 v19, 0x3f317217, v18
	v_cmp_lt_f32_e64 s[8:9], |v18|, s31
	s_nop 1
	v_cndmask_b32_e64 v18, v18, v19, s[8:9]
	v_cndmask_b32_e32 v19, 0, v227, vcc
	v_sub_f32_e32 v18, v18, v19
	v_add_f32_e32 v90, v88, v18
	v_mov_b32_e32 v18, v205
	s_waitcnt lgkmcnt(0)
	v_lshlrev_b32_e32 v18, 16, v18
	v_mul_f32_e32 v18, 0xbfb8aa3b, v18
	v_exp_f32_e32 v20, v18
	s_nop 0
	v_add_f32_e32 v18, 1.0, v20
	v_rcp_f32_e32 v18, v18
	s_nop 0
	v_fma_f32 v19, v0, v18, v89
	v_cmp_gt_f32_e32 vcc, s15, v19
	s_nop 1
	v_cndmask_b32_e64 v21, 0, 32, vcc
	v_ldexp_f32 v19, v19, v21
	v_log_f32_e32 v19, v19
	s_nop 0
	v_mul_f32_e32 v21, 0x3f317217, v19
	v_fma_f32 v21, v19, s30, -v21
	v_fmac_f32_e32 v21, 0x3377d1cf, v19
	v_fmac_f32_e32 v21, 0x3f317217, v19
	v_cmp_lt_f32_e64 s[8:9], |v19|, s31
	s_nop 1
	v_cndmask_b32_e64 v19, v19, v21, s[8:9]
	v_cndmask_b32_e32 v21, 0, v227, vcc
	v_sub_f32_e32 v19, v19, v21
	v_add_f32_e32 v91, v90, v19
	v_mov_b32_e32 v19, v206
	s_waitcnt lgkmcnt(0)
	v_lshlrev_b32_e32 v19, 16, v19
	v_mul_f32_e32 v19, 0xbfb8aa3b, v19
	v_exp_f32_e32 v21, v19
	s_nop 0
	v_add_f32_e32 v19, 1.0, v21
	v_rcp_f32_e32 v19, v19
	s_nop 0
	v_fma_f32 v22, v0, v19, v89
	v_cmp_gt_f32_e32 vcc, s15, v22
	s_nop 1
	v_cndmask_b32_e64 v23, 0, 32, vcc
	v_ldexp_f32 v22, v22, v23
	v_log_f32_e32 v22, v22
	s_nop 0
	v_mul_f32_e32 v23, 0x3f317217, v22
	v_fma_f32 v23, v22, s30, -v23
	v_fmac_f32_e32 v23, 0x3377d1cf, v22
	v_fmac_f32_e32 v23, 0x3f317217, v22
	v_cmp_lt_f32_e64 s[8:9], |v22|, s31
	s_nop 1
	v_cndmask_b32_e64 v22, v22, v23, s[8:9]
	v_cndmask_b32_e32 v23, 0, v227, vcc
	v_sub_f32_e32 v22, v22, v23
	v_add_f32_e32 v92, v91, v22
	v_mov_b32_e32 v22, v207
	s_waitcnt lgkmcnt(0)
	v_lshlrev_b32_e32 v22, 16, v22
	v_mul_f32_e32 v22, 0xbfb8aa3b, v22
	v_exp_f32_e32 v24, v22
	s_nop 0
	v_add_f32_e32 v22, 1.0, v24
	v_rcp_f32_e32 v22, v22
	s_nop 0
	v_fma_f32 v23, v0, v22, v89
	v_cmp_gt_f32_e32 vcc, s15, v23
	s_nop 1
	v_cndmask_b32_e64 v25, 0, 32, vcc
	v_ldexp_f32 v23, v23, v25
	v_log_f32_e32 v23, v23
	s_nop 0
	v_mul_f32_e32 v25, 0x3f317217, v23
	v_fma_f32 v25, v23, s30, -v25
	v_fmac_f32_e32 v25, 0x3377d1cf, v23
	v_fmac_f32_e32 v25, 0x3f317217, v23
	v_cmp_lt_f32_e64 s[8:9], |v23|, s31
	s_nop 1
	v_cndmask_b32_e64 v23, v23, v25, s[8:9]
	v_cndmask_b32_e32 v25, 0, v227, vcc
	v_sub_f32_e32 v23, v23, v25
	v_add_f32_e32 v93, v92, v23
	v_mov_b32_e32 v23, v216
	s_waitcnt lgkmcnt(0)
	v_lshlrev_b32_e32 v23, 16, v23
	v_mul_f32_e32 v23, 0xbfb8aa3b, v23
	v_exp_f32_e32 v25, v23
	s_nop 0
	v_add_f32_e32 v23, 1.0, v25
	v_rcp_f32_e32 v23, v23
	s_nop 0
	v_fma_f32 v26, v0, v23, v89
	v_cmp_gt_f32_e32 vcc, s15, v26
	s_nop 1
	v_cndmask_b32_e64 v27, 0, 32, vcc
	v_ldexp_f32 v26, v26, v27
	v_log_f32_e32 v26, v26
	s_nop 0
	v_mul_f32_e32 v27, 0x3f317217, v26
	v_fma_f32 v27, v26, s30, -v27
	v_fmac_f32_e32 v27, 0x3377d1cf, v26
	v_fmac_f32_e32 v27, 0x3f317217, v26
	v_cmp_lt_f32_e64 s[8:9], |v26|, s31
	s_nop 1
	v_cndmask_b32_e64 v26, v26, v27, s[8:9]
	v_cndmask_b32_e32 v27, 0, v227, vcc
	v_sub_f32_e32 v26, v26, v27
	v_add_f32_e32 v94, v93, v26
	v_mov_b32_e32 v26, v217
	s_waitcnt lgkmcnt(0)
	v_lshlrev_b32_e32 v26, 16, v26
	v_mul_f32_e32 v26, 0xbfb8aa3b, v26
	v_exp_f32_e32 v28, v26
	s_nop 0
	v_add_f32_e32 v26, 1.0, v28
	v_rcp_f32_e32 v26, v26
	s_nop 0
	v_fma_f32 v27, v0, v26, v89
	v_cmp_gt_f32_e32 vcc, s15, v27
	s_nop 1
	v_cndmask_b32_e64 v29, 0, 32, vcc
	v_ldexp_f32 v27, v27, v29
	v_log_f32_e32 v27, v27
	s_nop 0
	v_mul_f32_e32 v29, 0x3f317217, v27
	v_fma_f32 v29, v27, s30, -v29
	v_fmac_f32_e32 v29, 0x3377d1cf, v27
	v_fmac_f32_e32 v29, 0x3f317217, v27
	v_cmp_lt_f32_e64 s[8:9], |v27|, s31
	s_nop 1
	v_cndmask_b32_e64 v27, v27, v29, s[8:9]
	v_cndmask_b32_e32 v29, 0, v227, vcc
	v_sub_f32_e32 v27, v27, v29
	v_add_f32_e32 v95, v94, v27
	v_mov_b32_e32 v27, v218
	s_waitcnt lgkmcnt(0)
	v_lshlrev_b32_e32 v27, 16, v27
	v_mul_f32_e32 v27, 0xbfb8aa3b, v27
	v_exp_f32_e32 v29, v27
	s_nop 0
	v_add_f32_e32 v27, 1.0, v29
	v_rcp_f32_e32 v27, v27
	s_nop 0
	v_fma_f32 v30, v0, v27, v89
	v_cmp_gt_f32_e32 vcc, s15, v30
	s_nop 1
	v_cndmask_b32_e64 v31, 0, 32, vcc
	v_ldexp_f32 v30, v30, v31
	v_log_f32_e32 v30, v30
	s_nop 0
	v_mul_f32_e32 v31, 0x3f317217, v30
	v_fma_f32 v31, v30, s30, -v31
	v_fmac_f32_e32 v31, 0x3377d1cf, v30
	v_fmac_f32_e32 v31, 0x3f317217, v30
	v_cmp_lt_f32_e64 s[8:9], |v30|, s31
	s_nop 1
	v_cndmask_b32_e64 v30, v30, v31, s[8:9]
	v_cndmask_b32_e32 v31, 0, v227, vcc
	v_sub_f32_e32 v30, v30, v31
	v_add_f32_e32 v96, v95, v30
	v_mov_b32_e32 v30, v219
	s_waitcnt lgkmcnt(0)
	v_lshlrev_b32_e32 v30, 16, v30
	v_mul_f32_e32 v30, 0xbfb8aa3b, v30
	v_exp_f32_e32 v64, v30
	s_nop 0
	v_add_f32_e32 v30, 1.0, v64
	v_rcp_f32_e32 v30, v30
	s_nop 0
	v_fma_f32 v31, v0, v30, v89
	v_cmp_gt_f32_e32 vcc, s15, v31
	s_nop 1
	v_cndmask_b32_e64 v65, 0, 32, vcc
	v_ldexp_f32 v31, v31, v65
	v_log_f32_e32 v31, v31
	s_nop 0
	v_mul_f32_e32 v65, 0x3f317217, v31
	v_fma_f32 v65, v31, s30, -v65
	v_fmac_f32_e32 v65, 0x3377d1cf, v31
	v_fmac_f32_e32 v65, 0x3f317217, v31
	v_cmp_lt_f32_e64 s[8:9], |v31|, s31
	s_nop 1
	v_cndmask_b32_e64 v31, v31, v65, s[8:9]
	v_cndmask_b32_e32 v65, 0, v227, vcc
	v_sub_f32_e32 v31, v31, v65
	v_add_f32_e32 v97, v96, v31
	v_mov_b32_e32 v31, v220
	s_waitcnt lgkmcnt(0)
	v_lshlrev_b32_e32 v31, 16, v31
	v_mul_f32_e32 v31, 0xbfb8aa3b, v31
	v_exp_f32_e32 v65, v31
	s_nop 0
	v_add_f32_e32 v31, 1.0, v65
	v_rcp_f32_e32 v31, v31
	s_nop 0
	v_fmac_f32_e32 v89, v0, v31
	v_cmp_gt_f32_e32 vcc, s15, v89
	s_nop 1
	v_cndmask_b32_e64 v98, 0, 32, vcc
	v_ldexp_f32 v89, v89, v98
	v_log_f32_e32 v89, v89
	s_nop 0
	v_mul_f32_e32 v98, 0x3f317217, v89
	v_fma_f32 v98, v89, s30, -v98
	v_fmac_f32_e32 v98, 0x3377d1cf, v89
	v_fmac_f32_e32 v98, 0x3f317217, v89
	v_cmp_lt_f32_e64 s[8:9], |v89|, s31
	s_nop 1
	v_cndmask_b32_e64 v89, v89, v98, s[8:9]
	v_cndmask_b32_e32 v98, 0, v227, vcc
	v_sub_f32_e32 v89, v89, v98
	v_add_f32_e32 v89, v97, v89
	ds_write_b32 v71, v89 offset:36864
	s_waitcnt lgkmcnt(1)
	ds_write_b16 v72, v221 offset:18432
	ds_write_b16 v72, v223 offset:18434
	ds_write_b16 v72, v224 offset:18436
	ds_write_b16 v72, v225 offset:18438
	ds_write_b16 v72, v229 offset:18440
	ds_write_b16 v72, v230 offset:18442
	ds_write_b16 v72, v232 offset:18444
	ds_write_b16 v72, v239 offset:18446
	ds_write_b16 v72, v240 offset:18448
	ds_write_b16 v72, v241 offset:18450
	ds_write_b16 v72, v242 offset:18452
	ds_write_b16 v72, v243 offset:18454
	ds_write_b16 v72, v244 offset:18456
	ds_write_b16 v72, v245 offset:18458
	ds_write_b16 v72, v246 offset:18460
	ds_write_b16 v72, v247 offset:18462
	s_waitcnt lgkmcnt(0)
	s_barrier
	s_and_saveexec_b64 s[8:9], s[0:1]
	s_cbranch_execz .LBB0_551
	ds_read_b32 v61, v73 offset:37376
	s_waitcnt lgkmcnt(0)
	v_add_f32_e32 v61, 0, v61
	s_or_b64 exec, exec, s[8:9]
	s_and_saveexec_b64 s[8:9], s[2:3]
	s_cbranch_execnz .LBB0_552
